# out-proj epilogue: removed the now-unused per-element residual row address computation (60 of 63 elements), on top of v48
# speedup vs baseline: 1.0023x; 1.0023x over previous
; DI int crow(int i, int h) { return (i & 3) + 8 * (i >> 2) + 4 * h; }
; DI const float* xrow(CP p, const Ptrs& w, int l, int tok) {
;   int b = tok / TPB, i = tok - b * TPB;
;   if (l == 0) return i < CTXL ? p.in[2] + (size_t)(b * CTXL + i) * DM : p.in[0] + (size_t)(b * 8192 + i - CTXL) * DM;
;   return i < CTXL ? w.xc1 + (size_t)(b * CTXL + i) * DM : p.out + (size_t)(b * 8192 + i - CTXL) * DM;
; DI void phase_out(CP p, const Ptrs& w, int l, bf16_t* sA, bf16_t* sB) {
;     ...
;     for (int mi = 0; mi < 2; ++mi)
; #pragma unroll
;       for (int ni = 0; ni < 2; ++ni) {
;         int col = n0 + wn * 64 + ni * 32 + r;
;         float gt = gate[col];
; #pragma unroll
;         for (int i = 0; i < 16; ++i) {
;           int ii = ib + wm * 64 + mi * 32 + crow(i, h);
;           const float* src = xrow(p, w, l, b * TPB + ii);
;           float* dstp = isctx ? w.xc1 + (size_t)(b * CTXL + ii) * DM : p.out + (size_t)(b * 8192 + ii - CTXL) * DM;
;           dstp[col] = src[col] + gt * acc[mi][ni][i];
;         }
.LBB0_967:
	s_lshl_b32 s10, s39, 13
	s_addk_i32 s10, 0xff00
	s_lshl_b32 s11, s39, 8
	v_ashrrev_i32_e32 v67, 31, v66
	s_and_b64 s[4:5], s[4:5], exec
	v_lshlrev_b64 v[66:67], 13, v[66:67]
	s_cselect_b32 s39, s11, s10
	v_lshl_add_u64 v[70:71], v[70:71], 0, v[66:67]
	v_add_u32_e32 v66, s39, v72
	v_ashrrev_i32_e32 v67, 31, v66
	s_cselect_b32 s5, s13, s77
	s_cselect_b32 s4, s12, s76
	v_lshlrev_b64 v[66:67], 13, v[66:67]
	v_lshl_add_u64 v[72:73], s[4:5], 0, v[66:67]
	v_lshlrev_b64 v[66:67], 2, v[64:65]
	v_lshl_add_u64 v[70:71], v[70:71], 0, v[66:67]
	s_nop 0
	v_readfirstlane_b32 s100, v70
	v_readfirstlane_b32 s101, v71
	v_mbcnt_lo_u32_b32 v168, -1, 0
	v_mbcnt_hi_u32_b32 v168, -1, v168
	v_lshlrev_b32_e32 v168, 13, v168
	s_nop 2
	global_load_dword v169, v168, s[100:101]
	global_load_dword v169, v168, s[100:101] offset:128
	v_subrev_u32_e32 v170, s100, v70
	global_load_dword v194, v170, s[100:101]
	v_add_u32_e32 v171, 0x2000, v170
	global_load_dword v195, v171, s[100:101]
	v_add_u32_e32 v171, 0x4000, v170
	global_load_dword v196, v171, s[100:101]
	v_add_u32_e32 v171, 0x6000, v170
	global_load_dword v197, v171, s[100:101]
	v_add_u32_e32 v171, 0x10000, v170
	global_load_dword v198, v171, s[100:101]
	v_add_u32_e32 v171, 0x12000, v170
	global_load_dword v199, v171, s[100:101]
	v_add_u32_e32 v171, 0x14000, v170
	global_load_dword v200, v171, s[100:101]
	v_add_u32_e32 v171, 0x16000, v170
	global_load_dword v201, v171, s[100:101]
	v_add_u32_e32 v171, 0x20000, v170
	global_load_dword v202, v171, s[100:101]
	v_add_u32_e32 v171, 0x22000, v170
	global_load_dword v203, v171, s[100:101]
	v_add_u32_e32 v171, 0x24000, v170
	global_load_dword v204, v171, s[100:101]
	v_add_u32_e32 v171, 0x26000, v170
	global_load_dword v205, v171, s[100:101]
	v_add_u32_e32 v171, 0x30000, v170
	global_load_dword v206, v171, s[100:101]
	v_add_u32_e32 v171, 0x32000, v170
	global_load_dword v207, v171, s[100:101]
	v_add_u32_e32 v171, 0x34000, v170
	global_load_dword v208, v171, s[100:101]
	v_add_u32_e32 v171, 0x36000, v170
	global_load_dword v209, v171, s[100:101]
	v_add_u32_e32 v171, 0x80, v170
	global_load_dword v210, v171, s[100:101]
	v_add_u32_e32 v171, 0x2080, v170
	global_load_dword v211, v171, s[100:101]
	v_add_u32_e32 v171, 0x4080, v170
	global_load_dword v212, v171, s[100:101]
	v_add_u32_e32 v171, 0x6080, v170
	global_load_dword v213, v171, s[100:101]
	v_add_u32_e32 v171, 0x10080, v170
	global_load_dword v172, v171, s[100:101]
	v_add_u32_e32 v171, 0x12080, v170
	global_load_dword v173, v171, s[100:101]
	v_add_u32_e32 v171, 0x14080, v170
	global_load_dword v174, v171, s[100:101]
	v_add_u32_e32 v171, 0x16080, v170
	global_load_dword v175, v171, s[100:101]
	v_add_u32_e32 v171, 0x20080, v170
	global_load_dword v176, v171, s[100:101]
	v_add_u32_e32 v171, 0x22080, v170
	global_load_dword v177, v171, s[100:101]
	v_add_u32_e32 v171, 0x24080, v170
	global_load_dword v178, v171, s[100:101]
	v_add_u32_e32 v171, 0x26080, v170
	global_load_dword v179, v171, s[100:101]
	v_add_u32_e32 v171, 0x30080, v170
	global_load_dword v132, v171, s[100:101]
	v_add_u32_e32 v171, 0x32080, v170
	global_load_dword v133, v171, s[100:101]
	v_add_u32_e32 v171, 0x34080, v170
	global_load_dword v134, v171, s[100:101]
	v_add_u32_e32 v171, 0x36080, v170
	global_load_dword v135, v171, s[100:101]
	v_lshl_add_u64 v[70:71], v[72:73], 0, v[66:67]
	v_readlane_b32 s46, v254, 54
	v_readlane_b32 s47, v254, 55
	s_mov_b64 s[10:11], -1
	s_andn2_b64 vcc, exec, s[46:47]
	s_waitcnt vmcnt(31)
	v_fma_f32 v74, v48, v90, v194
	v_or_b32_e32 v48, v92, v167
	v_add_u32_e32 v72, s38, v48
	v_mul_hi_i32 v73, v72, s0
	global_store_dword v[70:71], v74, off
	v_lshrrev_b32_e32 v74, 31, v73
	v_ashrrev_i32_e32 v73, 11, v73
	v_add_u32_e32 v95, v73, v74
	v_mad_i32_i24 v96, v95, s1, v72
	v_cndmask_b32_e64 v72, 0, 1, s[46:47]
	v_cmp_lt_i32_e64 s[44:45], s37, v96
	v_cmp_ne_u32_e64 s[40:41], 1, v72
	v_add_u32_e32 v74, s39, v48
	v_ashrrev_i32_e32 v75, 31, v74
	v_lshlrev_b64 v[74:75], 13, v[74:75]
	v_lshl_add_u64 v[74:75], s[4:5], 0, v[74:75]
	v_lshl_add_u64 v[72:73], v[74:75], 0, v[66:67]
	v_or_b32_e32 v76, v92, v180
	s_mov_b64 s[10:11], -1
	s_and_b64 vcc, exec, s[40:41]
	s_waitcnt vmcnt(31)
	v_fma_f32 v48, v49, v90, v195
	global_store_dword v[72:73], v48, off
	v_add_u32_e32 v48, s38, v76
	v_mul_hi_i32 v49, v48, s0
	v_lshrrev_b32_e32 v74, 31, v49
	v_ashrrev_i32_e32 v49, 11, v49
	v_add_u32_e32 v97, v49, v74
	v_mad_i32_i24 v98, v97, s1, v48
	v_cmp_lt_i32_e64 s[46:47], s37, v98
	v_add_u32_e32 v74, s39, v76
	v_ashrrev_i32_e32 v75, 31, v74
	v_lshlrev_b64 v[74:75], 13, v[74:75]
	v_lshl_add_u64 v[74:75], s[4:5], 0, v[74:75]
	v_lshl_add_u64 v[74:75], v[74:75], 0, v[66:67]
	s_mov_b64 s[10:11], -1
	s_and_b64 vcc, exec, s[40:41]
	s_waitcnt vmcnt(31)
	v_fma_f32 v48, v50, v90, v196
	v_or_b32_e32 v50, v92, v181
	global_store_dword v[74:75], v48, off
	v_add_u32_e32 v48, s38, v50
	v_mul_hi_i32 v49, v48, s0
	v_lshrrev_b32_e32 v76, 31, v49
	v_ashrrev_i32_e32 v49, 11, v49
	v_add_u32_e32 v99, v49, v76
	v_mad_i32_i24 v100, v99, s1, v48
	v_cmp_lt_i32_e64 s[48:49], s37, v100
	v_add_u32_e32 v76, s39, v50
	v_ashrrev_i32_e32 v77, 31, v76
	v_lshlrev_b64 v[76:77], 13, v[76:77]
	v_lshl_add_u64 v[76:77], s[4:5], 0, v[76:77]
	v_or_b32_e32 v78, v92, v182
	s_mov_b64 s[10:11], -1
	s_and_b64 vcc, exec, s[40:41]
	s_waitcnt vmcnt(31)
	v_fma_f32 v48, v51, v90, v197
	v_lshl_add_u64 v[50:51], v[76:77], 0, v[66:67]
	global_store_dword v[50:51], v48, off
	v_add_u32_e32 v48, s38, v78
	v_mul_hi_i32 v49, v48, s0
	v_lshrrev_b32_e32 v76, 31, v49
	v_ashrrev_i32_e32 v49, 11, v49
	v_add_u32_e32 v101, v49, v76
	v_mad_i32_i24 v102, v101, s1, v48
	v_cmp_lt_i32_e64 s[50:51], s37, v102
	v_add_u32_e32 v76, s39, v78
	v_ashrrev_i32_e32 v77, 31, v76
	v_lshlrev_b64 v[76:77], 13, v[76:77]
	v_lshl_add_u64 v[76:77], s[4:5], 0, v[76:77]
	v_lshl_add_u64 v[76:77], v[76:77], 0, v[66:67]
	s_mov_b64 s[10:11], -1
	s_and_b64 vcc, exec, s[40:41]
	s_waitcnt vmcnt(31)
; DI int crow(int i, int h) { return (i & 3) + 8 * (i >> 2) + 4 * h; }
; DI const float* xrow(CP p, const Ptrs& w, int l, int tok) {
;   int b = tok / TPB, i = tok - b * TPB;
;   if (l == 0) return i < CTXL ? p.in[2] + (size_t)(b * CTXL + i) * DM : p.in[0] + (size_t)(b * 8192 + i - CTXL) * DM;
;   return i < CTXL ? w.xc1 + (size_t)(b * CTXL + i) * DM : p.out + (size_t)(b * 8192 + i - CTXL) * DM;
; DI void phase_out(CP p, const Ptrs& w, int l, bf16_t* sA, bf16_t* sB) {
;     ...
;     for (int mi = 0; mi < 2; ++mi)
; #pragma unroll
;       for (int ni = 0; ni < 2; ++ni) {
;         int col = n0 + wn * 64 + ni * 32 + r;
;         float gt = gate[col];
; #pragma unroll
;         for (int i = 0; i < 16; ++i) {
;           int ii = ib + wm * 64 + mi * 32 + crow(i, h);
;           const float* src = xrow(p, w, l, b * TPB + ii);
;           float* dstp = isctx ? w.xc1 + (size_t)(b * CTXL + ii) * DM : p.out + (size_t)(b * 8192 + ii - CTXL) * DM;
;           dstp[col] = src[col] + gt * acc[mi][ni][i];
;         }
	v_fma_f32 v48, v52, v90, v198
	v_or_b32_e32 v52, v92, v183
	global_store_dword v[76:77], v48, off
	v_add_u32_e32 v48, s38, v52
	v_mul_hi_i32 v49, v48, s0
	v_lshrrev_b32_e32 v78, 31, v49
	v_ashrrev_i32_e32 v49, 11, v49
	v_add_u32_e32 v103, v49, v78
	v_mad_i32_i24 v104, v103, s1, v48
	v_cmp_lt_i32_e64 s[52:53], s37, v104
	v_add_u32_e32 v78, s39, v52
	v_ashrrev_i32_e32 v79, 31, v78
	v_lshlrev_b64 v[78:79], 13, v[78:79]
	v_lshl_add_u64 v[78:79], s[4:5], 0, v[78:79]
	v_or_b32_e32 v80, v92, v184
	s_mov_b64 s[10:11], -1
	s_and_b64 vcc, exec, s[40:41]
	s_waitcnt vmcnt(31)
	v_fma_f32 v48, v53, v90, v199
	v_lshl_add_u64 v[52:53], v[78:79], 0, v[66:67]
	global_store_dword v[52:53], v48, off
	v_add_u32_e32 v48, s38, v80
	v_mul_hi_i32 v49, v48, s0
	v_lshrrev_b32_e32 v78, 31, v49
	v_ashrrev_i32_e32 v49, 11, v49
	v_add_u32_e32 v105, v49, v78
	v_mad_i32_i24 v106, v105, s1, v48
	v_cmp_lt_i32_e64 s[54:55], s37, v106
	v_add_u32_e32 v78, s39, v80
	v_ashrrev_i32_e32 v79, 31, v78
	v_lshlrev_b64 v[78:79], 13, v[78:79]
	v_lshl_add_u64 v[78:79], s[4:5], 0, v[78:79]
	v_lshl_add_u64 v[78:79], v[78:79], 0, v[66:67]
	s_mov_b64 s[10:11], -1
	s_and_b64 vcc, exec, s[40:41]
	s_waitcnt vmcnt(31)
	v_fma_f32 v48, v54, v90, v200
	v_or_b32_e32 v54, v92, v185
	global_store_dword v[78:79], v48, off
	v_add_u32_e32 v48, s38, v54
	v_mul_hi_i32 v49, v48, s0
	v_lshrrev_b32_e32 v80, 31, v49
	v_ashrrev_i32_e32 v49, 11, v49
	v_add_u32_e32 v107, v49, v80
	v_mad_i32_i24 v108, v107, s1, v48
	v_cmp_lt_i32_e64 s[56:57], s37, v108
	v_add_u32_e32 v80, s39, v54
	v_ashrrev_i32_e32 v81, 31, v80
	v_lshlrev_b64 v[80:81], 13, v[80:81]
	v_lshl_add_u64 v[80:81], s[4:5], 0, v[80:81]
	v_or_b32_e32 v82, v92, v186
	s_mov_b64 s[10:11], -1
	s_and_b64 vcc, exec, s[40:41]
	s_waitcnt vmcnt(31)
	v_fma_f32 v48, v55, v90, v201
	v_lshl_add_u64 v[54:55], v[80:81], 0, v[66:67]
	global_store_dword v[54:55], v48, off
	v_add_u32_e32 v48, s38, v82
	v_mul_hi_i32 v49, v48, s0
	v_lshrrev_b32_e32 v80, 31, v49
	v_ashrrev_i32_e32 v49, 11, v49
	v_add_u32_e32 v109, v49, v80
	v_mad_i32_i24 v110, v109, s1, v48
	v_cmp_lt_i32_e64 s[58:59], s37, v110
	v_add_u32_e32 v80, s39, v82
	v_ashrrev_i32_e32 v81, 31, v80
	v_lshlrev_b64 v[80:81], 13, v[80:81]
	v_lshl_add_u64 v[80:81], s[4:5], 0, v[80:81]
	v_lshl_add_u64 v[80:81], v[80:81], 0, v[66:67]
	s_mov_b64 s[10:11], -1
	s_and_b64 vcc, exec, s[40:41]
	s_waitcnt vmcnt(31)
	v_fma_f32 v48, v56, v90, v202
	v_or_b32_e32 v56, v92, v187
	global_store_dword v[80:81], v48, off
	v_add_u32_e32 v48, s38, v56
	v_mul_hi_i32 v49, v48, s0
	v_lshrrev_b32_e32 v82, 31, v49
	v_ashrrev_i32_e32 v49, 11, v49
	v_add_u32_e32 v111, v49, v82
	v_mad_i32_i24 v112, v111, s1, v48
	v_cmp_lt_i32_e64 s[60:61], s37, v112
	v_add_u32_e32 v82, s39, v56
	v_ashrrev_i32_e32 v83, 31, v82
	v_lshlrev_b64 v[82:83], 13, v[82:83]
	v_lshl_add_u64 v[82:83], s[4:5], 0, v[82:83]
	v_or_b32_e32 v84, v92, v188
	s_mov_b64 s[10:11], -1
	s_and_b64 vcc, exec, s[40:41]
	s_waitcnt vmcnt(31)
	v_fma_f32 v48, v57, v90, v203
	v_lshl_add_u64 v[56:57], v[82:83], 0, v[66:67]
	global_store_dword v[56:57], v48, off
	v_add_u32_e32 v48, s38, v84
	v_mul_hi_i32 v49, v48, s0
	v_lshrrev_b32_e32 v82, 31, v49
	v_ashrrev_i32_e32 v49, 11, v49
	v_add_u32_e32 v113, v49, v82
	v_mad_i32_i24 v114, v113, s1, v48
	v_cmp_lt_i32_e64 s[62:63], s37, v114
	v_add_u32_e32 v82, s39, v84
	v_ashrrev_i32_e32 v83, 31, v82
	v_lshlrev_b64 v[82:83], 13, v[82:83]
	v_lshl_add_u64 v[82:83], s[4:5], 0, v[82:83]
	v_lshl_add_u64 v[82:83], v[82:83], 0, v[66:67]
	s_mov_b64 s[10:11], -1
	s_and_b64 vcc, exec, s[40:41]
	s_waitcnt vmcnt(31)
	v_fma_f32 v48, v58, v90, v204
	v_or_b32_e32 v58, v92, v189
	global_store_dword v[82:83], v48, off
	v_add_u32_e32 v48, s38, v58
	v_mul_hi_i32 v49, v48, s0
	v_lshrrev_b32_e32 v84, 31, v49
	v_ashrrev_i32_e32 v49, 11, v49
	v_add_u32_e32 v115, v49, v84
	v_mad_i32_i24 v116, v115, s1, v48
	v_cmp_lt_i32_e64 s[64:65], s37, v116
	v_add_u32_e32 v84, s39, v58
	v_ashrrev_i32_e32 v85, 31, v84
	v_lshlrev_b64 v[84:85], 13, v[84:85]
	v_lshl_add_u64 v[84:85], s[4:5], 0, v[84:85]
	v_or_b32_e32 v86, v92, v190
	s_mov_b64 s[10:11], -1
	s_and_b64 vcc, exec, s[40:41]
	s_waitcnt vmcnt(31)
	v_fma_f32 v48, v59, v90, v205
	v_lshl_add_u64 v[58:59], v[84:85], 0, v[66:67]
	global_store_dword v[58:59], v48, off
	v_add_u32_e32 v48, s38, v86
	v_mul_hi_i32 v49, v48, s0
	v_lshrrev_b32_e32 v84, 31, v49
	v_ashrrev_i32_e32 v49, 11, v49
	v_add_u32_e32 v117, v49, v84
	v_mad_i32_i24 v118, v117, s1, v48
	v_cmp_lt_i32_e64 s[66:67], s37, v118
	v_add_u32_e32 v84, s39, v86
	v_ashrrev_i32_e32 v85, 31, v84
	v_lshlrev_b64 v[84:85], 13, v[84:85]
	v_lshl_add_u64 v[84:85], s[4:5], 0, v[84:85]
	v_lshl_add_u64 v[84:85], v[84:85], 0, v[66:67]
	s_mov_b64 s[10:11], -1
	s_and_b64 vcc, exec, s[40:41]
	s_waitcnt vmcnt(31)
	v_fma_f32 v48, v60, v90, v206
	v_or_b32_e32 v60, v92, v191
	global_store_dword v[84:85], v48, off
	v_add_u32_e32 v48, s38, v60
	v_mul_hi_i32 v49, v48, s0
	v_lshrrev_b32_e32 v86, 31, v49
	v_ashrrev_i32_e32 v49, 11, v49
	v_add_u32_e32 v119, v49, v86
	v_mad_i32_i24 v120, v119, s1, v48
	v_cmp_lt_i32_e64 s[68:69], s37, v120
	v_add_u32_e32 v86, s39, v60
	v_ashrrev_i32_e32 v87, 31, v86
	v_lshlrev_b64 v[86:87], 13, v[86:87]
	v_lshl_add_u64 v[86:87], s[4:5], 0, v[86:87]
	v_or_b32_e32 v88, v92, v192
	s_mov_b64 s[10:11], -1
	s_and_b64 vcc, exec, s[40:41]
	s_waitcnt vmcnt(31)
	v_fma_f32 v48, v61, v90, v207
	v_lshl_add_u64 v[60:61], v[86:87], 0, v[66:67]
	global_store_dword v[60:61], v48, off
	v_add_u32_e32 v48, s38, v88
	v_mul_hi_i32 v49, v48, s0
	v_lshrrev_b32_e32 v86, 31, v49
	v_ashrrev_i32_e32 v49, 11, v49
	v_add_u32_e32 v121, v49, v86
	v_mad_i32_i24 v122, v121, s1, v48
	v_cmp_lt_i32_e64 s[70:71], s37, v122
	v_add_u32_e32 v86, s39, v88
	v_ashrrev_i32_e32 v87, 31, v86
	v_lshlrev_b64 v[86:87], 13, v[86:87]
	v_lshl_add_u64 v[86:87], s[4:5], 0, v[86:87]
	v_lshl_add_u64 v[86:87], v[86:87], 0, v[66:67]
	s_mov_b64 s[10:11], -1
	s_and_b64 vcc, exec, s[40:41]
	s_waitcnt vmcnt(31)
	v_fma_f32 v48, v62, v90, v208
	v_or_b32_e32 v62, v92, v193
	global_store_dword v[86:87], v48, off
	v_add_u32_e32 v48, s38, v62
	v_mul_hi_i32 v49, v48, s0
	v_lshrrev_b32_e32 v88, 31, v49
	v_ashrrev_i32_e32 v49, 11, v49
	v_add_u32_e32 v123, v49, v88
	v_mad_i32_i24 v124, v123, s1, v48
	v_cmp_lt_i32_e64 s[72:73], s37, v124
	s_cbranch_vccnz .LBB0_1141
	s_and_saveexec_b64 s[10:11], s[72:73]
	s_xor_b64 s[10:11], exec, s[10:11]
	v_lshlrev_b32_e32 v48, 13, v123
	s_movk_i32 vcc_lo, 0xff00
	v_add3_u32 v48, v48, v124, vcc_lo
	s_or_saveexec_b64 s[10:11], s[10:11]
	v_mov_b64_e32 v[88:89], s[76:77]
	s_xor_b64 exec, exec, s[10:11]
	v_lshl_add_u32 v48, v123, 8, v124
	v_mov_b64_e32 v[88:89], s[12:13]
	s_or_b64 exec, exec, s[10:11]
	s_mov_b64 s[10:11], 0

; DI int crow(int i, int h) { return (i & 3) + 8 * (i >> 2) + 4 * h; }
; DI const float* xrow(CP p, const Ptrs& w, int l, int tok) {
;   int b = tok / TPB, i = tok - b * TPB;
;   if (l == 0) return i < CTXL ? p.in[2] + (size_t)(b * CTXL + i) * DM : p.in[0] + (size_t)(b * 8192 + i - CTXL) * DM;
;   return i < CTXL ? w.xc1 + (size_t)(b * CTXL + i) * DM : p.out + (size_t)(b * 8192 + i - CTXL) * DM;
; DI void phase_out(CP p, const Ptrs& w, int l, bf16_t* sA, bf16_t* sB) {
;     ...
;     const float* gate = w.mod + (l * 3 + (isctx ? 2 : b)) * 6144 + 4096;
; #pragma unroll
;     for (int mi = 0; mi < 2; ++mi)
; #pragma unroll
;       for (int ni = 0; ni < 2; ++ni) {
;         int col = n0 + wn * 64 + ni * 32 + r;
;         float gt = gate[col];
; #pragma unroll
;         for (int i = 0; i < 16; ++i) {
;           int ii = ib + wm * 64 + mi * 32 + crow(i, h);
;           const float* src = xrow(p, w, l, b * TPB + ii);
;           float* dstp = isctx ? w.xc1 + (size_t)(b * CTXL + ii) * DM : p.out + (size_t)(b * 8192 + ii - CTXL) * DM;
;           dstp[col] = src[col] + gt * acc[mi][ni][i];
;         }
;       }
.LBB0_1147:
	v_ashrrev_i32_e32 v49, 31, v48
	v_lshlrev_b64 v[48:49], 13, v[48:49]
	v_lshl_add_u64 v[48:49], v[88:89], 0, v[48:49]
	v_lshl_add_u64 v[48:49], v[48:49], 0, v[66:67]
	v_add_u32_e32 v48, s39, v62
	v_ashrrev_i32_e32 v49, 31, v48
	v_lshlrev_b64 v[48:49], 13, v[48:49]
	v_or_b32_e32 v126, 32, v64
	v_lshl_add_u64 v[48:49], s[4:5], 0, v[48:49]
	v_ashrrev_i32_e32 v127, 31, v126
	v_lshl_add_u64 v[88:89], v[48:49], 0, v[66:67]
	v_lshl_add_u64 v[48:49], v[126:127], 2, s[6:7]
	s_and_b64 vcc, exec, s[40:41]
	s_mov_b64 s[6:7], -1
	s_waitcnt vmcnt(31)
	v_fma_f32 v91, v63, v90, v209
	global_store_dword v[88:89], v91, off
	s_waitcnt vmcnt(32)
	v_add_u32_e32 v171, 0x40000, v170
	global_load_dword v194, v171, s[100:101]
	v_add_u32_e32 v171, 0x42000, v170
	global_load_dword v195, v171, s[100:101]
	v_add_u32_e32 v171, 0x44000, v170
	global_load_dword v196, v171, s[100:101]
	v_add_u32_e32 v171, 0x46000, v170
	global_load_dword v197, v171, s[100:101]
	v_add_u32_e32 v171, 0x50000, v170
	global_load_dword v198, v171, s[100:101]
	v_add_u32_e32 v171, 0x52000, v170
	global_load_dword v199, v171, s[100:101]
	v_add_u32_e32 v171, 0x54000, v170
	global_load_dword v200, v171, s[100:101]
	v_add_u32_e32 v171, 0x56000, v170
	global_load_dword v201, v171, s[100:101]
	v_add_u32_e32 v171, 0x60000, v170
	global_load_dword v202, v171, s[100:101]
	v_add_u32_e32 v171, 0x62000, v170
	global_load_dword v203, v171, s[100:101]
	v_add_u32_e32 v171, 0x64000, v170
	global_load_dword v204, v171, s[100:101]
	v_add_u32_e32 v171, 0x66000, v170
	global_load_dword v205, v171, s[100:101]
	v_add_u32_e32 v171, 0x70000, v170
	global_load_dword v206, v171, s[100:101]
	v_add_u32_e32 v171, 0x72000, v170
	global_load_dword v207, v171, s[100:101]
	v_add_u32_e32 v171, 0x74000, v170
	global_load_dword v208, v171, s[100:101]
	v_add_u32_e32 v171, 0x76000, v170
	global_load_dword v209, v171, s[100:101]
	global_load_dword v125, v[48:49], off
	s_and_b64 vcc, exec, s[40:41]
	s_mov_b64 s[6:7], -1
	s_waitcnt vmcnt(0)
	v_fma_f32 v62, v32, v125, v210
	global_store_dword v[70:71], v62, off offset:128
	s_and_b64 vcc, exec, s[40:41]
	s_mov_b64 s[6:7], -1
	s_waitcnt vmcnt(1)
	v_fma_f32 v32, v33, v125, v211
	global_store_dword v[72:73], v32, off offset:128
	s_and_b64 vcc, exec, s[40:41]
	s_mov_b64 s[6:7], -1
	s_waitcnt vmcnt(2)
	v_fma_f32 v32, v34, v125, v212
	global_store_dword v[74:75], v32, off offset:128
	s_and_b64 vcc, exec, s[40:41]
	s_mov_b64 s[6:7], -1
	s_waitcnt vmcnt(3)
	v_fma_f32 v32, v35, v125, v213
	global_store_dword v[50:51], v32, off offset:128
	s_and_b64 vcc, exec, s[40:41]
	s_mov_b64 s[6:7], -1
	s_waitcnt vmcnt(4)
	v_fma_f32 v32, v36, v125, v172
	global_store_dword v[76:77], v32, off offset:128
	s_and_b64 vcc, exec, s[40:41]
	s_mov_b64 s[6:7], -1
	s_waitcnt vmcnt(5)
	v_fma_f32 v32, v37, v125, v173
	global_store_dword v[52:53], v32, off offset:128
	s_and_b64 vcc, exec, s[40:41]
	s_mov_b64 s[6:7], -1
	s_waitcnt vmcnt(6)
	v_fma_f32 v32, v38, v125, v174
	global_store_dword v[78:79], v32, off offset:128
	s_and_b64 vcc, exec, s[40:41]
	s_mov_b64 s[6:7], -1
	s_waitcnt vmcnt(7)
	v_fma_f32 v32, v39, v125, v175
	global_store_dword v[54:55], v32, off offset:128
	s_and_b64 vcc, exec, s[40:41]
	s_mov_b64 s[6:7], -1
	s_waitcnt vmcnt(8)
	v_fma_f32 v32, v40, v125, v176
	global_store_dword v[80:81], v32, off offset:128
	s_and_b64 vcc, exec, s[40:41]
	s_mov_b64 s[6:7], -1
	s_waitcnt vmcnt(9)
	v_fma_f32 v32, v41, v125, v177
	global_store_dword v[56:57], v32, off offset:128
	s_and_b64 vcc, exec, s[40:41]
	s_mov_b64 s[6:7], -1
	s_waitcnt vmcnt(10)
	v_fma_f32 v32, v42, v125, v178
	global_store_dword v[82:83], v32, off offset:128
	s_and_b64 vcc, exec, s[40:41]
	s_mov_b64 s[6:7], -1
	s_waitcnt vmcnt(11)
	v_fma_f32 v32, v43, v125, v179
	global_store_dword v[58:59], v32, off offset:128
	s_and_b64 vcc, exec, s[40:41]
	s_mov_b64 s[6:7], -1
	s_waitcnt vmcnt(12)
	v_fma_f32 v32, v44, v125, v132
	global_store_dword v[84:85], v32, off offset:128
	s_and_b64 vcc, exec, s[40:41]
	s_mov_b64 s[6:7], -1
	s_waitcnt vmcnt(13)
	v_fma_f32 v32, v45, v125, v133
	global_store_dword v[60:61], v32, off offset:128
	s_and_b64 vcc, exec, s[40:41]
	s_mov_b64 s[6:7], -1
	s_waitcnt vmcnt(14)
	v_fma_f32 v32, v46, v125, v134
	global_store_dword v[86:87], v32, off offset:128
	s_cbranch_vccnz .LBB0_1333
	s_and_saveexec_b64 s[6:7], s[72:73]
	s_xor_b64 s[6:7], exec, s[6:7]
	v_lshlrev_b32_e32 v32, 13, v123
	s_movk_i32 s10, 0xff00
	v_add3_u32 v32, v32, v124, s10
	s_or_saveexec_b64 s[6:7], s[6:7]
	v_mov_b64_e32 v[34:35], s[76:77]
	s_xor_b64 exec, exec, s[6:7]
	v_lshl_add_u32 v32, v123, 8, v124
	v_mov_b64_e32 v[34:35], s[12:13]
	s_or_b64 exec, exec, s[6:7]
	s_mov_b64 s[6:7], 0

; DI int crow(int i, int h) { return (i & 3) + 8 * (i >> 2) + 4 * h; }
; DI void phase_out(CP p, const Ptrs& w, int l, bf16_t* sA, bf16_t* sB) {
;     ...
;     const float* gate = w.mod + (l * 3 + (isctx ? 2 : b)) * 6144 + 4096;
; #pragma unroll
;     for (int mi = 0; mi < 2; ++mi)
; #pragma unroll
;       for (int ni = 0; ni < 2; ++ni) {
;         int col = n0 + wn * 64 + ni * 32 + r;
;         float gt = gate[col];
; #pragma unroll
;         for (int i = 0; i < 16; ++i) {
;           int ii = ib + wm * 64 + mi * 32 + crow(i, h);
;           const float* src = xrow(p, w, l, b * TPB + ii);
;           float* dstp = isctx ? w.xc1 + (size_t)(b * CTXL + ii) * DM : p.out + (size_t)(b * 8192 + ii - CTXL) * DM;
;           dstp[col] = src[col] + gt * acc[mi][ni][i];
;         }
;       }
.LBB0_1339:
	v_ashrrev_i32_e32 v33, 31, v32
	v_lshlrev_b64 v[32:33], 13, v[32:33]
	v_lshl_add_u64 v[32:33], v[34:35], 0, v[32:33]
	v_lshl_add_u64 v[32:33], v[64:65], 2, v[32:33]
	v_or_b32_e32 v52, 32, v92
	v_or_b32_e32 v36, v52, v164
	s_and_b64 vcc, exec, s[40:41]
	s_mov_b64 s[6:7], -1
	s_waitcnt vmcnt(15)
	v_fma_f32 v32, v47, v125, v135
	global_store_dword v[88:89], v32, off offset:128
	s_waitcnt vmcnt(32)
	v_add_u32_e32 v171, 0x40080, v170
	global_load_dword v210, v171, s[100:101]
	v_add_u32_e32 v171, 0x42080, v170
	global_load_dword v211, v171, s[100:101]
	v_add_u32_e32 v171, 0x44080, v170
	global_load_dword v212, v171, s[100:101]
	v_add_u32_e32 v171, 0x46080, v170
	global_load_dword v213, v171, s[100:101]
	v_add_u32_e32 v171, 0x50080, v170
	global_load_dword v172, v171, s[100:101]
	v_add_u32_e32 v171, 0x52080, v170
	global_load_dword v173, v171, s[100:101]
	v_add_u32_e32 v171, 0x54080, v170
	global_load_dword v174, v171, s[100:101]
	v_add_u32_e32 v171, 0x56080, v170
	global_load_dword v175, v171, s[100:101]
	v_add_u32_e32 v171, 0x60080, v170
	global_load_dword v176, v171, s[100:101]
	v_add_u32_e32 v171, 0x62080, v170
	global_load_dword v177, v171, s[100:101]
	v_add_u32_e32 v171, 0x64080, v170
	global_load_dword v178, v171, s[100:101]
	v_add_u32_e32 v171, 0x66080, v170
	global_load_dword v179, v171, s[100:101]
	v_add_u32_e32 v171, 0x70080, v170
	global_load_dword v132, v171, s[100:101]
	v_add_u32_e32 v171, 0x72080, v170
	global_load_dword v133, v171, s[100:101]
	v_add_u32_e32 v171, 0x74080, v170
	global_load_dword v134, v171, s[100:101]
	global_load_dword v58, v[68:69], off
	v_add_u32_e32 v32, s38, v36
	v_mul_hi_i32 v33, v32, s0
	v_lshrrev_b32_e32 v34, 31, v33
	v_ashrrev_i32_e32 v33, 11, v33
	v_add_u32_e32 v54, v33, v34
	v_mad_i32_i24 v55, v54, s1, v32
	v_cmp_lt_i32_e64 s[42:43], s37, v55
	v_add_u32_e32 v34, s39, v36
	v_ashrrev_i32_e32 v35, 31, v34
	v_lshlrev_b64 v[34:35], 13, v[34:35]
	v_lshl_add_u64 v[34:35], s[4:5], 0, v[34:35]
	v_lshl_add_u64 v[32:33], v[34:35], 0, v[66:67]
	s_mov_b64 s[6:7], -1
	s_and_b64 vcc, exec, s[40:41]
	s_waitcnt vmcnt(0)
	v_fma_f32 v36, v16, v58, v194
	v_or_b32_e32 v16, v52, v167
	v_add_u32_e32 v34, s38, v16
	v_mul_hi_i32 v35, v34, s0
	global_store_dword v[32:33], v36, off
	v_lshrrev_b32_e32 v36, 31, v35
	v_ashrrev_i32_e32 v35, 11, v35
	v_add_u32_e32 v56, v35, v36
	v_mad_i32_i24 v57, v56, s1, v34
	v_cmp_lt_i32_e64 s[44:45], s37, v57
	v_add_u32_e32 v36, s39, v16
	v_ashrrev_i32_e32 v37, 31, v36
	v_lshlrev_b64 v[36:37], 13, v[36:37]
	v_lshl_add_u64 v[36:37], s[4:5], 0, v[36:37]
	v_or_b32_e32 v38, v52, v180
	s_mov_b64 s[6:7], -1
	s_and_b64 vcc, exec, s[40:41]
	s_waitcnt vmcnt(1)
	v_fma_f32 v34, v17, v58, v195
	v_lshl_add_u64 v[16:17], v[36:37], 0, v[66:67]
	global_store_dword v[16:17], v34, off
	v_add_u32_e32 v34, s38, v38
	v_mul_hi_i32 v35, v34, s0
	v_lshrrev_b32_e32 v36, 31, v35
	v_ashrrev_i32_e32 v35, 11, v35
	v_add_u32_e32 v59, v35, v36
	v_mad_i32_i24 v60, v59, s1, v34
	v_cmp_lt_i32_e64 s[46:47], s37, v60
	v_add_u32_e32 v36, s39, v38
	v_ashrrev_i32_e32 v37, 31, v36
	v_lshlrev_b64 v[36:37], 13, v[36:37]
	v_lshl_add_u64 v[36:37], s[4:5], 0, v[36:37]
	v_lshl_add_u64 v[34:35], v[36:37], 0, v[66:67]
	s_mov_b64 s[6:7], -1
	s_and_b64 vcc, exec, s[40:41]
	s_waitcnt vmcnt(2)
	v_fma_f32 v38, v18, v58, v196
	v_or_b32_e32 v18, v52, v181
	v_add_u32_e32 v36, s38, v18
	v_mul_hi_i32 v37, v36, s0
	global_store_dword v[34:35], v38, off
	v_lshrrev_b32_e32 v38, 31, v37
	v_ashrrev_i32_e32 v37, 11, v37
	v_add_u32_e32 v61, v37, v38
	v_mad_i32_i24 v62, v61, s1, v36
	v_cmp_lt_i32_e64 s[48:49], s37, v62
	v_add_u32_e32 v38, s39, v18
	v_ashrrev_i32_e32 v39, 31, v38
	v_lshlrev_b64 v[38:39], 13, v[38:39]
	v_lshl_add_u64 v[38:39], s[4:5], 0, v[38:39]
	v_or_b32_e32 v40, v52, v182
	s_mov_b64 s[6:7], -1
	s_and_b64 vcc, exec, s[40:41]
	s_waitcnt vmcnt(3)
	v_fma_f32 v36, v19, v58, v197
	v_lshl_add_u64 v[18:19], v[38:39], 0, v[66:67]
	global_store_dword v[18:19], v36, off
	v_add_u32_e32 v36, s38, v40
	v_mul_hi_i32 v37, v36, s0
	v_lshrrev_b32_e32 v38, 31, v37
	v_ashrrev_i32_e32 v37, 11, v37
	v_add_u32_e32 v63, v37, v38
	v_mad_i32_i24 v68, v63, s1, v36
	v_cmp_lt_i32_e64 s[50:51], s37, v68
	v_add_u32_e32 v38, s39, v40
	v_ashrrev_i32_e32 v39, 31, v38
	v_lshlrev_b64 v[38:39], 13, v[38:39]
	v_lshl_add_u64 v[38:39], s[4:5], 0, v[38:39]
	v_lshl_add_u64 v[36:37], v[38:39], 0, v[66:67]
	s_mov_b64 s[6:7], -1
	s_and_b64 vcc, exec, s[40:41]
	s_waitcnt vmcnt(4)
	v_fma_f32 v40, v20, v58, v198
	v_or_b32_e32 v20, v52, v183
	v_add_u32_e32 v38, s38, v20
	v_mul_hi_i32 v39, v38, s0
	global_store_dword v[36:37], v40, off
	v_lshrrev_b32_e32 v40, 31, v39
	v_ashrrev_i32_e32 v39, 11, v39
	v_add_u32_e32 v69, v39, v40
	v_mad_i32_i24 v70, v69, s1, v38
	v_cmp_lt_i32_e64 s[52:53], s37, v70
	v_add_u32_e32 v40, s39, v20
	v_ashrrev_i32_e32 v41, 31, v40
	v_lshlrev_b64 v[40:41], 13, v[40:41]
	v_lshl_add_u64 v[40:41], s[4:5], 0, v[40:41]
	v_or_b32_e32 v42, v52, v184
	s_mov_b64 s[6:7], -1
	s_and_b64 vcc, exec, s[40:41]
	s_waitcnt vmcnt(5)
	v_fma_f32 v38, v21, v58, v199
	v_lshl_add_u64 v[20:21], v[40:41], 0, v[66:67]
	global_store_dword v[20:21], v38, off
	v_add_u32_e32 v38, s38, v42
	v_mul_hi_i32 v39, v38, s0
	v_lshrrev_b32_e32 v40, 31, v39
	v_ashrrev_i32_e32 v39, 11, v39
	v_add_u32_e32 v71, v39, v40
	v_mad_i32_i24 v72, v71, s1, v38
	v_cmp_lt_i32_e64 s[54:55], s37, v72
	v_add_u32_e32 v40, s39, v42
	v_ashrrev_i32_e32 v41, 31, v40
	v_lshlrev_b64 v[40:41], 13, v[40:41]
	v_lshl_add_u64 v[40:41], s[4:5], 0, v[40:41]
	v_lshl_add_u64 v[38:39], v[40:41], 0, v[66:67]
	s_mov_b64 s[6:7], -1
	s_and_b64 vcc, exec, s[40:41]
	s_waitcnt vmcnt(6)
; DI int crow(int i, int h) { return (i & 3) + 8 * (i >> 2) + 4 * h; }
; DI void phase_out(CP p, const Ptrs& w, int l, bf16_t* sA, bf16_t* sB) {
;     ...
;     const float* gate = w.mod + (l * 3 + (isctx ? 2 : b)) * 6144 + 4096;
; #pragma unroll
;     for (int mi = 0; mi < 2; ++mi)
; #pragma unroll
;       for (int ni = 0; ni < 2; ++ni) {
;         int col = n0 + wn * 64 + ni * 32 + r;
;         float gt = gate[col];
; #pragma unroll
;         for (int i = 0; i < 16; ++i) {
;           int ii = ib + wm * 64 + mi * 32 + crow(i, h);
;           const float* src = xrow(p, w, l, b * TPB + ii);
;           float* dstp = isctx ? w.xc1 + (size_t)(b * CTXL + ii) * DM : p.out + (size_t)(b * 8192 + ii - CTXL) * DM;
;           dstp[col] = src[col] + gt * acc[mi][ni][i];
;         }
;       }
	v_fma_f32 v42, v22, v58, v200
	v_or_b32_e32 v22, v52, v185
	v_add_u32_e32 v40, s38, v22
	v_mul_hi_i32 v41, v40, s0
	global_store_dword v[38:39], v42, off
	v_lshrrev_b32_e32 v42, 31, v41
	v_ashrrev_i32_e32 v41, 11, v41
	v_add_u32_e32 v73, v41, v42
	v_mad_i32_i24 v74, v73, s1, v40
	v_cmp_lt_i32_e64 s[56:57], s37, v74
	v_add_u32_e32 v42, s39, v22
	v_ashrrev_i32_e32 v43, 31, v42
	v_lshlrev_b64 v[42:43], 13, v[42:43]
	v_lshl_add_u64 v[42:43], s[4:5], 0, v[42:43]
	v_or_b32_e32 v44, v52, v186
	s_mov_b64 s[6:7], -1
	s_and_b64 vcc, exec, s[40:41]
	s_waitcnt vmcnt(7)
	v_fma_f32 v40, v23, v58, v201
	v_lshl_add_u64 v[22:23], v[42:43], 0, v[66:67]
	global_store_dword v[22:23], v40, off
	v_add_u32_e32 v40, s38, v44
	v_mul_hi_i32 v41, v40, s0
	v_lshrrev_b32_e32 v42, 31, v41
	v_ashrrev_i32_e32 v41, 11, v41
	v_add_u32_e32 v75, v41, v42
	v_mad_i32_i24 v76, v75, s1, v40
	v_cmp_lt_i32_e64 s[58:59], s37, v76
	v_add_u32_e32 v42, s39, v44
	v_ashrrev_i32_e32 v43, 31, v42
	v_lshlrev_b64 v[42:43], 13, v[42:43]
	v_lshl_add_u64 v[42:43], s[4:5], 0, v[42:43]
	v_lshl_add_u64 v[40:41], v[42:43], 0, v[66:67]
	s_mov_b64 s[6:7], -1
	s_and_b64 vcc, exec, s[40:41]
	s_waitcnt vmcnt(8)
	v_fma_f32 v44, v24, v58, v202
	v_or_b32_e32 v24, v52, v187
	v_add_u32_e32 v42, s38, v24
	v_mul_hi_i32 v43, v42, s0
	global_store_dword v[40:41], v44, off
	v_lshrrev_b32_e32 v44, 31, v43
	v_ashrrev_i32_e32 v43, 11, v43
	v_add_u32_e32 v77, v43, v44
	v_mad_i32_i24 v78, v77, s1, v42
	v_cmp_lt_i32_e64 s[60:61], s37, v78
	v_add_u32_e32 v44, s39, v24
	v_ashrrev_i32_e32 v45, 31, v44
	v_lshlrev_b64 v[44:45], 13, v[44:45]
	v_lshl_add_u64 v[44:45], s[4:5], 0, v[44:45]
	v_or_b32_e32 v46, v52, v188
	s_mov_b64 s[6:7], -1
	s_and_b64 vcc, exec, s[40:41]
	s_waitcnt vmcnt(9)
	v_fma_f32 v42, v25, v58, v203
	v_lshl_add_u64 v[24:25], v[44:45], 0, v[66:67]
	global_store_dword v[24:25], v42, off
	v_add_u32_e32 v42, s38, v46
	v_mul_hi_i32 v43, v42, s0
	v_lshrrev_b32_e32 v44, 31, v43
	v_ashrrev_i32_e32 v43, 11, v43
	v_add_u32_e32 v79, v43, v44
	v_mad_i32_i24 v80, v79, s1, v42
	v_cmp_lt_i32_e64 s[62:63], s37, v80
	v_add_u32_e32 v44, s39, v46
	v_ashrrev_i32_e32 v45, 31, v44
	v_lshlrev_b64 v[44:45], 13, v[44:45]
	v_lshl_add_u64 v[44:45], s[4:5], 0, v[44:45]
	v_lshl_add_u64 v[42:43], v[44:45], 0, v[66:67]
	s_mov_b64 s[6:7], -1
	s_and_b64 vcc, exec, s[40:41]
	s_waitcnt vmcnt(10)
	v_fma_f32 v46, v26, v58, v204
	v_or_b32_e32 v26, v52, v189
	v_add_u32_e32 v44, s38, v26
	v_mul_hi_i32 v45, v44, s0
	global_store_dword v[42:43], v46, off
	v_lshrrev_b32_e32 v46, 31, v45
	v_ashrrev_i32_e32 v45, 11, v45
	v_add_u32_e32 v81, v45, v46
	v_mad_i32_i24 v82, v81, s1, v44
	v_cmp_lt_i32_e64 s[64:65], s37, v82
	v_add_u32_e32 v46, s39, v26
	v_ashrrev_i32_e32 v47, 31, v46
	v_lshlrev_b64 v[46:47], 13, v[46:47]
	v_lshl_add_u64 v[46:47], s[4:5], 0, v[46:47]
	v_or_b32_e32 v50, v52, v190
	s_mov_b64 s[6:7], -1
	s_and_b64 vcc, exec, s[40:41]
	s_waitcnt vmcnt(11)
	v_fma_f32 v44, v27, v58, v205
	v_lshl_add_u64 v[26:27], v[46:47], 0, v[66:67]
	global_store_dword v[26:27], v44, off
	v_add_u32_e32 v44, s38, v50
	v_mul_hi_i32 v45, v44, s0
	v_lshrrev_b32_e32 v46, 31, v45
	v_ashrrev_i32_e32 v45, 11, v45
	v_add_u32_e32 v83, v45, v46
	v_mad_i32_i24 v84, v83, s1, v44
	v_cmp_lt_i32_e64 s[66:67], s37, v84
	v_add_u32_e32 v46, s39, v50
	v_ashrrev_i32_e32 v47, 31, v46
	v_lshlrev_b64 v[46:47], 13, v[46:47]
	v_lshl_add_u64 v[46:47], s[4:5], 0, v[46:47]
	v_lshl_add_u64 v[44:45], v[46:47], 0, v[66:67]
	s_mov_b64 s[6:7], -1
	s_and_b64 vcc, exec, s[40:41]
	s_waitcnt vmcnt(12)
	v_fma_f32 v50, v28, v58, v206
	v_or_b32_e32 v28, v52, v191
	v_add_u32_e32 v46, s38, v28
	v_mul_hi_i32 v47, v46, s0
	global_store_dword v[44:45], v50, off
	v_lshrrev_b32_e32 v50, 31, v47
	v_ashrrev_i32_e32 v47, 11, v47
	v_add_u32_e32 v85, v47, v50
	v_mad_i32_i24 v86, v85, s1, v46
	v_cmp_lt_i32_e64 s[68:69], s37, v86
	v_add_u32_e32 v50, s39, v28
	v_ashrrev_i32_e32 v51, 31, v50
	v_lshlrev_b64 v[50:51], 13, v[50:51]
	v_lshl_add_u64 v[50:51], s[4:5], 0, v[50:51]
	v_or_b32_e32 v53, v52, v192
	s_mov_b64 s[6:7], -1
	s_and_b64 vcc, exec, s[40:41]
	s_waitcnt vmcnt(13)
; DI int crow(int i, int h) { return (i & 3) + 8 * (i >> 2) + 4 * h; }
; DI void phase_out(CP p, const Ptrs& w, int l, bf16_t* sA, bf16_t* sB) {
;     ...
;     const float* gate = w.mod + (l * 3 + (isctx ? 2 : b)) * 6144 + 4096;
; #pragma unroll
;     for (int mi = 0; mi < 2; ++mi)
; #pragma unroll
;       for (int ni = 0; ni < 2; ++ni) {
;         int col = n0 + wn * 64 + ni * 32 + r;
;         float gt = gate[col];
; #pragma unroll
;         for (int i = 0; i < 16; ++i) {
;           int ii = ib + wm * 64 + mi * 32 + crow(i, h);
;           const float* src = xrow(p, w, l, b * TPB + ii);
;           float* dstp = isctx ? w.xc1 + (size_t)(b * CTXL + ii) * DM : p.out + (size_t)(b * 8192 + ii - CTXL) * DM;
;           dstp[col] = src[col] + gt * acc[mi][ni][i];
;         }
;       }
	v_fma_f32 v46, v29, v58, v207
	v_lshl_add_u64 v[28:29], v[50:51], 0, v[66:67]
	global_store_dword v[28:29], v46, off
	v_add_u32_e32 v46, s38, v53
	v_mul_hi_i32 v47, v46, s0
	v_lshrrev_b32_e32 v50, 31, v47
	v_ashrrev_i32_e32 v47, 11, v47
	v_add_u32_e32 v87, v47, v50
	v_mad_i32_i24 v88, v87, s1, v46
	v_cmp_lt_i32_e64 s[70:71], s37, v88
	v_add_u32_e32 v50, s39, v53
	v_ashrrev_i32_e32 v51, 31, v50
	v_lshlrev_b64 v[50:51], 13, v[50:51]
	v_lshl_add_u64 v[50:51], s[4:5], 0, v[50:51]
	v_lshl_add_u64 v[46:47], v[50:51], 0, v[66:67]
	s_mov_b64 s[6:7], -1
	s_and_b64 vcc, exec, s[40:41]
	s_waitcnt vmcnt(14)
	v_fma_f32 v53, v30, v58, v208
	v_or_b32_e32 v30, v52, v193
	v_add_u32_e32 v50, s38, v30
	v_mul_hi_i32 v51, v50, s0
	v_lshrrev_b32_e32 v52, 31, v51
	v_ashrrev_i32_e32 v51, 11, v51
	v_add_u32_e32 v89, v51, v52
	v_mad_i32_i24 v90, v89, s1, v50
	v_cmp_lt_i32_e64 s[72:73], s37, v90
	global_store_dword v[46:47], v53, off
	v_add_u32_e32 v50, s39, v30
	v_ashrrev_i32_e32 v51, 31, v50
	v_lshlrev_b64 v[50:51], 13, v[50:51]
	v_lshl_add_u64 v[50:51], s[4:5], 0, v[50:51]
	s_and_b64 vcc, exec, s[40:41]
	s_mov_b64 s[4:5], -1
	s_waitcnt vmcnt(15)
	v_fma_f32 v52, v31, v58, v209
	v_lshl_add_u64 v[30:31], v[50:51], 0, v[66:67]
	global_store_dword v[30:31], v52, off
	global_load_dword v52, v[48:49], off
	s_and_b64 vcc, exec, s[40:41]
	s_mov_b64 s[4:5], -1
	v_readlane_b32 s42, v255, 3
	s_waitcnt vmcnt(0)
	v_fma_f32 v48, v0, v52, v210
	global_store_dword v[32:33], v48, off offset:128
	s_and_b64 vcc, exec, s[40:41]
	s_mov_b64 s[4:5], -1
	s_waitcnt vmcnt(1)
	v_fma_f32 v0, v1, v52, v211
	global_store_dword v[16:17], v0, off offset:128
	s_and_b64 vcc, exec, s[40:41]
	s_mov_b64 s[4:5], -1
	s_waitcnt vmcnt(2)
	v_fma_f32 v0, v2, v52, v212
	global_store_dword v[34:35], v0, off offset:128
	s_and_b64 vcc, exec, s[40:41]
	s_mov_b64 s[4:5], -1
	s_waitcnt vmcnt(3)
	v_fma_f32 v0, v3, v52, v213
	global_store_dword v[18:19], v0, off offset:128
	s_and_b64 vcc, exec, s[40:41]
	s_mov_b64 s[4:5], -1
	s_waitcnt vmcnt(4)
	v_fma_f32 v0, v4, v52, v172
	global_store_dword v[36:37], v0, off offset:128
	s_and_b64 vcc, exec, s[40:41]
	s_mov_b64 s[4:5], -1
	s_waitcnt vmcnt(5)
	v_fma_f32 v0, v5, v52, v173
	global_store_dword v[20:21], v0, off offset:128
	s_and_b64 vcc, exec, s[40:41]
	s_mov_b64 s[4:5], -1
	s_waitcnt vmcnt(6)
	v_fma_f32 v0, v6, v52, v174
	global_store_dword v[38:39], v0, off offset:128
	s_and_b64 vcc, exec, s[40:41]
	s_mov_b64 s[4:5], -1
	s_waitcnt vmcnt(7)
	v_fma_f32 v0, v7, v52, v175
	global_store_dword v[22:23], v0, off offset:128
	s_and_b64 vcc, exec, s[40:41]
	s_mov_b64 s[4:5], -1
	s_waitcnt vmcnt(8)
	v_fma_f32 v0, v8, v52, v176
	global_store_dword v[40:41], v0, off offset:128
	s_and_b64 vcc, exec, s[40:41]
	s_mov_b64 s[4:5], -1
	v_readlane_b32 s61, v254, 51
	s_waitcnt vmcnt(9)
	v_fma_f32 v0, v9, v52, v177
	global_store_dword v[24:25], v0, off offset:128
	s_and_b64 vcc, exec, s[40:41]
	s_mov_b64 s[4:5], -1
	s_waitcnt vmcnt(10)
	v_fma_f32 v0, v10, v52, v178
	global_store_dword v[42:43], v0, off offset:128
	s_and_b64 vcc, exec, s[40:41]
	s_mov_b64 s[4:5], -1
	s_waitcnt vmcnt(11)
	v_fma_f32 v0, v11, v52, v179
	global_store_dword v[26:27], v0, off offset:128
	s_and_b64 vcc, exec, s[40:41]
	s_mov_b64 s[4:5], -1
	s_waitcnt vmcnt(12)
	v_fma_f32 v0, v12, v52, v132
	global_store_dword v[44:45], v0, off offset:128
	s_and_b64 vcc, exec, s[40:41]
	s_mov_b64 s[4:5], -1
	s_waitcnt vmcnt(13)
	v_fma_f32 v0, v13, v52, v133
	global_store_dword v[28:29], v0, off offset:128
	s_and_b64 vcc, exec, s[40:41]
	s_mov_b64 s[4:5], -1
	v_readlane_b32 s41, v255, 1
	s_waitcnt vmcnt(14)
	v_fma_f32 v0, v14, v52, v134
	global_store_dword v[46:47], v0, off offset:128
	s_cbranch_vccnz .LBB0_1717
	s_and_saveexec_b64 s[4:5], s[72:73]
	s_xor_b64 s[4:5], exec, s[4:5]
	v_lshlrev_b32_e32 v0, 13, v89
	s_movk_i32 s6, 0xff00
	v_add3_u32 v0, v0, v90, s6
	s_or_saveexec_b64 s[4:5], s[4:5]
	v_mov_b64_e32 v[2:3], s[76:77]
	s_xor_b64 exec, exec, s[4:5]
	v_lshl_add_u32 v0, v89, 8, v90
	v_mov_b64_e32 v[2:3], s[12:13]
	s_or_b64 exec, exec, s[4:5]
	s_mov_b64 s[4:5], 0
